# pool item final MFMA stage rewritten: per weight group all 14 LDS reads issued up front, counted waits, 8 MFMAs back to back, stores via immediate offsets
# baseline (speedup 1.0000x reference)
.LBB0_730:
	v_or_b32_e32 v2, s4, v11
	v_mul_lo_u32 v2, v2, s72
	v_and_b32_e32 v13, 48, v60
	v_lshlrev_b64 v[0:1], 11, v[0:1]
	v_mul_u32_u24_e32 v11, 0x90, v11
	v_readlane_b32 s4, v255, 50
	v_add3_u32 v12, 0, v2, v13
	v_lshl_add_u64 v[0:1], s[42:43], 0, v[0:1]
	s_mov_b64 s[10:11], 0x4a40600
	v_add3_u32 v11, s4, v13, v11
	v_lshl_add_u64 v[8:9], v[0:1], 0, s[10:11]
	s_add_i32 s4, 0, 0x25400
	v_lshl_add_u32 v13, v61, 4, s4
	v_lshlrev_b32_e32 v174, 3, v61
	v_lshl_add_u64 v[22:23], v[8:9], 0, v[174:175]
	ds_read_b128 v[0:3], v12 offset:48128
	ds_read_b128 v[4:7], v12 offset:48192
	ds_read_b128 v[184:187], v11
	ds_read_b128 v[188:191], v11 offset:64
	ds_read_b128 v[192:195], v11 offset:2304
	ds_read_b128 v[196:199], v11 offset:2368
	ds_read_b128 v[200:203], v11 offset:4608
	ds_read_b128 v[204:207], v11 offset:4672
	ds_read_b128 v[208:211], v11 offset:6912
	ds_read_b128 v[212:215], v11 offset:6976
	ds_read_b128 v[216:219], v13
	ds_read_b128 v[220:223], v13 offset:64
	ds_read_b128 v[224:227], v13 offset:128
	ds_read_b128 v[228:231], v13 offset:192
	s_waitcnt lgkmcnt(11)
	v_mfma_f32_16x16x32_bf16 v[14:17], v[184:187], v[0:3], 0
	s_waitcnt lgkmcnt(10)
	v_mfma_f32_16x16x32_bf16 v[14:17], v[188:191], v[4:7], v[14:17]
	s_waitcnt lgkmcnt(9)
	v_mfma_f32_16x16x32_bf16 v[18:21], v[192:195], v[0:3], 0
	s_waitcnt lgkmcnt(8)
	v_mfma_f32_16x16x32_bf16 v[18:21], v[196:199], v[4:7], v[18:21]
	s_waitcnt lgkmcnt(7)
	v_mfma_f32_16x16x32_bf16 v[152:155], v[200:203], v[0:3], 0
	s_waitcnt lgkmcnt(6)
	v_mfma_f32_16x16x32_bf16 v[152:155], v[204:207], v[4:7], v[152:155]
	s_waitcnt lgkmcnt(5)
	v_mfma_f32_16x16x32_bf16 v[156:159], v[208:211], v[0:3], 0
	s_waitcnt lgkmcnt(4)
	v_mfma_f32_16x16x32_bf16 v[156:159], v[212:215], v[4:7], v[156:159]
	s_waitcnt lgkmcnt(0)
	s_nop 7
	v_pk_mul_f32 v[14:15], v[14:15], v[216:217]
	v_pk_mul_f32 v[16:17], v[16:17], v[218:219]
	v_cvt_pk_bf16_f32 v14, v14, v15
	v_cvt_pk_bf16_f32 v15, v16, v17
	global_store_dwordx2 v[22:23], v[14:15], off
	v_pk_mul_f32 v[18:19], v[18:19], v[220:221]
	v_pk_mul_f32 v[20:21], v[20:21], v[222:223]
	v_cvt_pk_bf16_f32 v18, v18, v19
	v_cvt_pk_bf16_f32 v19, v20, v21
	global_store_dwordx2 v[22:23], v[18:19], off offset:32
	v_pk_mul_f32 v[152:153], v[152:153], v[224:225]
	v_pk_mul_f32 v[154:155], v[154:155], v[226:227]
	v_cvt_pk_bf16_f32 v152, v152, v153
	v_cvt_pk_bf16_f32 v153, v154, v155
	global_store_dwordx2 v[22:23], v[152:153], off offset:64
	s_nop 1
	v_pk_mul_f32 v[156:157], v[156:157], v[228:229]
	v_pk_mul_f32 v[158:159], v[158:159], v[230:231]
	v_cvt_pk_bf16_f32 v156, v156, v157
	v_cvt_pk_bf16_f32 v157, v158, v159
	global_store_dwordx2 v[22:23], v[156:157], off offset:96
	ds_read_b128 v[0:3], v12 offset:48256
	ds_read_b128 v[4:7], v12 offset:48320
	ds_read_b128 v[184:187], v11 offset:9216
	ds_read_b128 v[188:191], v11 offset:9280
	ds_read_b128 v[192:195], v11 offset:11520
	ds_read_b128 v[196:199], v11 offset:11584
	ds_read_b128 v[200:203], v11 offset:13824
	ds_read_b128 v[204:207], v11 offset:13888
	ds_read_b128 v[208:211], v11 offset:16128
	ds_read_b128 v[212:215], v11 offset:16192
	ds_read_b128 v[216:219], v13 offset:256
	ds_read_b128 v[220:223], v13 offset:320
	ds_read_b128 v[224:227], v13 offset:384
	ds_read_b128 v[228:231], v13 offset:448
	s_waitcnt lgkmcnt(11)
	v_mfma_f32_16x16x32_bf16 v[14:17], v[184:187], v[0:3], 0
	s_waitcnt lgkmcnt(10)
	v_mfma_f32_16x16x32_bf16 v[14:17], v[188:191], v[4:7], v[14:17]
	s_waitcnt lgkmcnt(9)
	v_mfma_f32_16x16x32_bf16 v[18:21], v[192:195], v[0:3], 0
	s_waitcnt lgkmcnt(8)
	v_mfma_f32_16x16x32_bf16 v[18:21], v[196:199], v[4:7], v[18:21]
	s_waitcnt lgkmcnt(7)
	v_mfma_f32_16x16x32_bf16 v[152:155], v[200:203], v[0:3], 0
	s_waitcnt lgkmcnt(6)
	v_mfma_f32_16x16x32_bf16 v[152:155], v[204:207], v[4:7], v[152:155]
	s_waitcnt lgkmcnt(5)
	v_mfma_f32_16x16x32_bf16 v[156:159], v[208:211], v[0:3], 0
	s_waitcnt lgkmcnt(4)
	v_mfma_f32_16x16x32_bf16 v[156:159], v[212:215], v[4:7], v[156:159]
	s_waitcnt lgkmcnt(0)
	s_nop 7
	v_pk_mul_f32 v[14:15], v[14:15], v[216:217]
	v_pk_mul_f32 v[16:17], v[16:17], v[218:219]
	v_cvt_pk_bf16_f32 v14, v14, v15
	v_cvt_pk_bf16_f32 v15, v16, v17
	global_store_dwordx2 v[22:23], v[14:15], off offset:128
	v_pk_mul_f32 v[18:19], v[18:19], v[220:221]
	v_pk_mul_f32 v[20:21], v[20:21], v[222:223]
	v_cvt_pk_bf16_f32 v18, v18, v19
	v_cvt_pk_bf16_f32 v19, v20, v21
	global_store_dwordx2 v[22:23], v[18:19], off offset:160
	v_pk_mul_f32 v[152:153], v[152:153], v[224:225]
	v_pk_mul_f32 v[154:155], v[154:155], v[226:227]
	v_cvt_pk_bf16_f32 v152, v152, v153
	v_cvt_pk_bf16_f32 v153, v154, v155
	global_store_dwordx2 v[22:23], v[152:153], off offset:192
	s_nop 1
	v_pk_mul_f32 v[156:157], v[156:157], v[228:229]
	v_pk_mul_f32 v[158:159], v[158:159], v[230:231]
	v_cvt_pk_bf16_f32 v156, v156, v157
	v_cvt_pk_bf16_f32 v157, v158, v159
	global_store_dwordx2 v[22:23], v[156:157], off offset:224
	ds_read_b128 v[0:3], v12 offset:48384
	ds_read_b128 v[4:7], v12 offset:48448
	ds_read_b128 v[184:187], v11 offset:18432
	ds_read_b128 v[188:191], v11 offset:18496
	ds_read_b128 v[192:195], v11 offset:20736
	ds_read_b128 v[196:199], v11 offset:20800
	ds_read_b128 v[200:203], v11 offset:23040
	ds_read_b128 v[204:207], v11 offset:23104
	ds_read_b128 v[208:211], v11 offset:25344
	ds_read_b128 v[212:215], v11 offset:25408
	ds_read_b128 v[216:219], v13 offset:512
	ds_read_b128 v[220:223], v13 offset:576
	ds_read_b128 v[224:227], v13 offset:640
	ds_read_b128 v[228:231], v13 offset:704
	s_waitcnt lgkmcnt(11)
	v_mfma_f32_16x16x32_bf16 v[14:17], v[184:187], v[0:3], 0
	s_waitcnt lgkmcnt(10)
	v_mfma_f32_16x16x32_bf16 v[14:17], v[188:191], v[4:7], v[14:17]
	s_waitcnt lgkmcnt(9)
	v_mfma_f32_16x16x32_bf16 v[18:21], v[192:195], v[0:3], 0
	s_waitcnt lgkmcnt(8)
	v_mfma_f32_16x16x32_bf16 v[18:21], v[196:199], v[4:7], v[18:21]
	s_waitcnt lgkmcnt(7)
	v_mfma_f32_16x16x32_bf16 v[152:155], v[200:203], v[0:3], 0
	s_waitcnt lgkmcnt(6)
	v_mfma_f32_16x16x32_bf16 v[152:155], v[204:207], v[4:7], v[152:155]
	s_waitcnt lgkmcnt(5)
	v_mfma_f32_16x16x32_bf16 v[156:159], v[208:211], v[0:3], 0
	s_waitcnt lgkmcnt(4)
	v_mfma_f32_16x16x32_bf16 v[156:159], v[212:215], v[4:7], v[156:159]
	s_waitcnt lgkmcnt(0)
	s_nop 7
	v_pk_mul_f32 v[14:15], v[14:15], v[216:217]
	v_pk_mul_f32 v[16:17], v[16:17], v[218:219]
	v_cvt_pk_bf16_f32 v14, v14, v15
	v_cvt_pk_bf16_f32 v15, v16, v17
	global_store_dwordx2 v[22:23], v[14:15], off offset:256
	v_pk_mul_f32 v[18:19], v[18:19], v[220:221]
	v_pk_mul_f32 v[20:21], v[20:21], v[222:223]
	v_cvt_pk_bf16_f32 v18, v18, v19
	v_cvt_pk_bf16_f32 v19, v20, v21
	global_store_dwordx2 v[22:23], v[18:19], off offset:288
	v_pk_mul_f32 v[152:153], v[152:153], v[224:225]
	v_pk_mul_f32 v[154:155], v[154:155], v[226:227]
	v_cvt_pk_bf16_f32 v152, v152, v153
	v_cvt_pk_bf16_f32 v153, v154, v155
	global_store_dwordx2 v[22:23], v[152:153], off offset:320
	s_nop 1
	v_pk_mul_f32 v[156:157], v[156:157], v[228:229]
	v_pk_mul_f32 v[158:159], v[158:159], v[230:231]
	v_cvt_pk_bf16_f32 v156, v156, v157
	v_cvt_pk_bf16_f32 v157, v158, v159
	global_store_dwordx2 v[22:23], v[156:157], off offset:352
	ds_read_b128 v[0:3], v12 offset:48512
	ds_read_b128 v[4:7], v12 offset:48576
	ds_read_b128 v[184:187], v11 offset:27648
	ds_read_b128 v[188:191], v11 offset:27712
	ds_read_b128 v[192:195], v11 offset:29952
	ds_read_b128 v[196:199], v11 offset:30016
	ds_read_b128 v[200:203], v11 offset:32256
	ds_read_b128 v[204:207], v11 offset:32320
	ds_read_b128 v[208:211], v11 offset:34560
	ds_read_b128 v[212:215], v11 offset:34624
	ds_read_b128 v[216:219], v13 offset:768
	ds_read_b128 v[220:223], v13 offset:832
	ds_read_b128 v[224:227], v13 offset:896
	ds_read_b128 v[228:231], v13 offset:960
	s_waitcnt lgkmcnt(11)
	v_mfma_f32_16x16x32_bf16 v[14:17], v[184:187], v[0:3], 0
	s_waitcnt lgkmcnt(10)
	v_mfma_f32_16x16x32_bf16 v[14:17], v[188:191], v[4:7], v[14:17]
	s_waitcnt lgkmcnt(9)
	v_mfma_f32_16x16x32_bf16 v[18:21], v[192:195], v[0:3], 0
	s_waitcnt lgkmcnt(8)
	v_mfma_f32_16x16x32_bf16 v[18:21], v[196:199], v[4:7], v[18:21]
	s_waitcnt lgkmcnt(7)
	v_mfma_f32_16x16x32_bf16 v[152:155], v[200:203], v[0:3], 0
	s_waitcnt lgkmcnt(6)
	v_mfma_f32_16x16x32_bf16 v[152:155], v[204:207], v[4:7], v[152:155]
	s_waitcnt lgkmcnt(5)
	v_mfma_f32_16x16x32_bf16 v[156:159], v[208:211], v[0:3], 0
	s_waitcnt lgkmcnt(4)
	v_mfma_f32_16x16x32_bf16 v[156:159], v[212:215], v[4:7], v[156:159]
	s_waitcnt lgkmcnt(0)
	s_nop 7
	v_pk_mul_f32 v[14:15], v[14:15], v[216:217]
	v_pk_mul_f32 v[16:17], v[16:17], v[218:219]
	v_cvt_pk_bf16_f32 v14, v14, v15
	v_cvt_pk_bf16_f32 v15, v16, v17
	global_store_dwordx2 v[22:23], v[14:15], off offset:384
	v_pk_mul_f32 v[18:19], v[18:19], v[220:221]
	v_pk_mul_f32 v[20:21], v[20:21], v[222:223]
	v_cvt_pk_bf16_f32 v18, v18, v19
	v_cvt_pk_bf16_f32 v19, v20, v21
	global_store_dwordx2 v[22:23], v[18:19], off offset:416
	v_pk_mul_f32 v[152:153], v[152:153], v[224:225]
	v_pk_mul_f32 v[154:155], v[154:155], v[226:227]
	v_cvt_pk_bf16_f32 v152, v152, v153
	v_cvt_pk_bf16_f32 v153, v154, v155
	global_store_dwordx2 v[22:23], v[152:153], off offset:448
	s_nop 1
	v_pk_mul_f32 v[156:157], v[156:157], v[228:229]
	v_pk_mul_f32 v[158:159], v[158:159], v[230:231]
	v_cvt_pk_bf16_f32 v156, v156, v157
	v_cvt_pk_bf16_f32 v157, v158, v159
	global_store_dwordx2 v[22:23], v[156:157], off offset:480
